# v004 + LN row loops P2 and P10: per-j scale/shift vectors preloaded up front instead of 16 dependent round trips per row
# speedup vs baseline: 1.0075x; 1.0025x over previous
; #define GAS __attribute__((address_space(1)))
; __device__ __forceinline__ void ln_stats(const v4f (&v)[16], float& mean, float& rstd) {
;     float s = 0.f;
; #pragma unroll
;     for (int j = 0; j < 16; ++j) s += (v[j].x + v[j].y) + (v[j].z + v[j].w);
;     mean = wave_sum(s) * (1.f / D_MODEL); float s2 = 0.f;
; __device__ __forceinline__ void phase_h(const Ctx& X, const float* x, const float* mod, bf16* h) {
;     for (int m = X.gw; m < MTOK; m += X.NGW) {
;         const GAS v4f* xr = (const GAS v4f*)(x + (size_t)m * D_MODEL) + X.lane;
;         v4f v[16];
; #pragma unroll
;         for (int j = 0; j < 16; ++j) v[j] = xr[64 * j];
;         float mean, rstd; ln_stats(v, mean, rstd);
.LBB0_91:
	global_load_dwordx4 v[12:15], v[72:73], off
	global_load_dwordx4 v[8:11], v[72:73], off offset:1024
	global_load_dwordx4 v[4:7], v[72:73], off offset:2048
	global_load_dwordx4 v[0:3], v[72:73], off offset:3072
	v_add_co_u32_e32 v16, vcc, 0x1000, v72
	s_ashr_i32 s2, s4, 31
	s_nop 0
	v_addc_co_u32_e32 v17, vcc, 0, v73, vcc
	global_load_dwordx4 v[60:63], v[16:17], off
	global_load_dwordx4 v[56:59], v[16:17], off offset:1024
	global_load_dwordx4 v[52:55], v[16:17], off offset:2048
	global_load_dwordx4 v[48:51], v[16:17], off offset:3072
	v_add_co_u32_e32 v18, vcc, 0x2000, v72
	s_lshr_b32 s2, s2, 20
	s_nop 0
	v_addc_co_u32_e32 v19, vcc, 0, v73, vcc
	global_load_dwordx4 v[44:47], v[18:19], off
	global_load_dwordx4 v[40:43], v[18:19], off offset:1024
	global_load_dwordx4 v[36:39], v[18:19], off offset:2048
	global_load_dwordx4 v[32:35], v[18:19], off offset:3072
	v_add_co_u32_e32 v16, vcc, 0x3000, v72
	s_add_i32 s2, s4, s2
	s_nop 0
	v_addc_co_u32_e32 v17, vcc, 0, v73, vcc
	global_load_dwordx4 v[28:31], v[16:17], off
	global_load_dwordx4 v[24:27], v[16:17], off offset:1024
	global_load_dwordx4 v[20:23], v[16:17], off offset:2048
	s_nop 0
	global_load_dwordx4 v[16:19], v[16:17], off offset:3072
	s_ashr_i32 s2, s2, 12
	s_mul_hi_i32 s3, s2, 0x18000
	s_mul_i32 s2, s2, 0x18000
	s_add_u32 s14, s16, s2
	s_addc_u32 s15, s17, s3
	s_add_u32 s52, s14, 0x4000
	s_addc_u32 s53, s15, 0
	s_add_u32 s54, s14, 0x5000
	s_addc_u32 s55, s15, 0
	s_add_u32 s56, s14, 0x6000
	s_addc_u32 s57, s15, 0
	s_add_u32 s58, s14, 0x7000
	s_addc_u32 s59, s15, 0
	s_add_u32 s60, s14, 0x0
	s_addc_u32 s61, s15, 0
	s_add_u32 s62, s14, 0x1000
	s_addc_u32 s63, s15, 0
	s_add_u32 s64, s14, 0x2000
	s_addc_u32 s65, s15, 0
	s_add_u32 s66, s14, 0x3000
	s_addc_u32 s67, s15, 0
	v_lshl_add_u64 v[74:75], s[14:15], 0, v[68:69]
	v_add_co_u32_e32 v76, vcc, s20, v74
	v_lshl_add_u64 v[78:79], v[74:75], 0, s[12:13]
	s_nop 0
	v_addc_co_u32_e32 v77, vcc, 0, v75, vcc
	global_load_dwordx4 v[90:93], v[76:77], off offset:-4096
	global_load_dwordx4 v[64:67], v68, s[14:15]
	global_load_dwordx4 v[138:141], v68, s[52:53] offset:1024
	global_load_dwordx4 v[142:145], v68, s[60:61] offset:1024
	global_load_dwordx4 v[146:149], v68, s[52:53] offset:2048
	global_load_dwordx4 v[150:153], v68, s[60:61] offset:2048
	global_load_dwordx4 v[154:157], v68, s[52:53] offset:3072
	global_load_dwordx4 v[158:161], v68, s[60:61] offset:3072
	global_load_dwordx4 v[162:165], v68, s[54:55]
	global_load_dwordx4 v[166:169], v68, s[62:63]
	global_load_dwordx4 v[170:173], v68, s[54:55] offset:1024
	global_load_dwordx4 v[174:177], v68, s[62:63] offset:1024
	global_load_dwordx4 v[178:181], v68, s[54:55] offset:2048
	global_load_dwordx4 v[182:185], v68, s[62:63] offset:2048
	global_load_dwordx4 v[186:189], v68, s[54:55] offset:3072
	global_load_dwordx4 v[190:193], v68, s[62:63] offset:3072
	global_load_dwordx4 v[194:197], v68, s[56:57]
	global_load_dwordx4 v[198:201], v68, s[64:65]
	global_load_dwordx4 v[202:205], v68, s[56:57] offset:1024
	global_load_dwordx4 v[206:209], v68, s[64:65] offset:1024
	global_load_dwordx4 v[210:213], v68, s[56:57] offset:2048
	global_load_dwordx4 v[214:217], v68, s[64:65] offset:2048
	global_load_dwordx4 v[218:221], v68, s[56:57] offset:3072
	global_load_dwordx4 v[222:225], v68, s[64:65] offset:3072
	global_load_dwordx4 v[226:229], v68, s[58:59]
	global_load_dwordx4 v[230:233], v68, s[66:67]
	global_load_dwordx4 v[234:237], v68, s[58:59] offset:1024
	global_load_dwordx4 v[238:241], v68, s[66:67] offset:1024
	global_load_dwordx4 v[242:245], v68, s[58:59] offset:2048
	global_load_dwordx4 v[246:249], v68, s[66:67] offset:2048
	s_add_i32 s4, s4, s6
	v_lshl_add_u64 v[72:73], v[72:73], 0, s[10:11]
	s_cmpk_lt_i32 s4, 0x4000
	s_waitcnt vmcnt(45)
	v_mov_b32_e32 v80, v13
	v_mov_b32_e32 v81, v14
	v_mov_b32_e32 v94, v12
	v_mov_b32_e32 v95, v15
	s_waitcnt vmcnt(44)
	v_mov_b32_e32 v96, v9
	v_mov_b32_e32 v97, v10
	v_mov_b32_e32 v98, v8
	v_mov_b32_e32 v99, v11
	v_pk_add_f32 v[80:81], v[80:81], v[94:95]
	v_pk_add_f32 v[94:95], v[96:97], v[98:99]
	v_add_f32_e32 v104, v80, v81
	v_pk_add_f32 v[80:81], v[94:95], v[94:95] op_sel:[0,1] op_sel_hi:[1,0]
	s_waitcnt vmcnt(43)
	v_add_f32_e32 v100, v4, v5
	v_add_f32_e32 v102, v6, v7
	s_waitcnt vmcnt(42)
	v_mov_b32_e32 v101, v2
	v_mov_b32_e32 v103, v3
	v_mov_b32_e32 v105, v0
	v_add_f32_e32 v104, 0, v104
	v_mov_b32_e32 v81, v1
	v_pk_add_f32 v[96:97], v[100:101], v[102:103]
	s_waitcnt vmcnt(41)
	v_mov_b32_e32 v98, v61
	v_mov_b32_e32 v99, v62
	v_mov_b32_e32 v100, v60
	v_mov_b32_e32 v101, v63
	v_pk_add_f32 v[80:81], v[104:105], v[80:81]
	v_pk_add_f32 v[94:95], v[98:99], v[100:101]
	v_pk_add_f32 v[80:81], v[80:81], v[96:97]
	v_pk_add_f32 v[94:95], v[94:95], v[94:95] op_sel:[0,1] op_sel_hi:[1,0]
	v_pk_add_f32 v[80:81], v[80:81], v[80:81] op_sel:[0,1] op_sel_hi:[1,0]
	s_waitcnt vmcnt(40)
	v_add_f32_e32 v102, v56, v57
	v_add_f32_e32 v106, v58, v59
	s_waitcnt vmcnt(39)
	v_mov_b32_e32 v103, v54
	v_mov_b32_e32 v107, v55
	v_mov_b32_e32 v95, v53
	v_mov_b32_e32 v81, v52
	s_waitcnt vmcnt(38)
	v_mov_b32_e32 v108, v49
	v_mov_b32_e32 v109, v50
	v_mov_b32_e32 v110, v48
	v_mov_b32_e32 v111, v51
	v_pk_add_f32 v[98:99], v[102:103], v[106:107]
	v_pk_add_f32 v[80:81], v[80:81], v[94:95]
	v_pk_add_f32 v[100:101], v[108:109], v[110:111]
	v_pk_add_f32 v[80:81], v[80:81], v[98:99]
	v_pk_add_f32 v[100:101], v[100:101], v[100:101] op_sel:[0,1] op_sel_hi:[1,0]
	v_pk_add_f32 v[80:81], v[80:81], v[80:81] op_sel:[0,1] op_sel_hi:[1,0]
	s_waitcnt vmcnt(37)
	v_add_f32_e32 v102, v44, v45
	s_waitcnt vmcnt(36)
	v_mov_b32_e32 v103, v42
	v_add_f32_e32 v106, v46, v47
	v_mov_b32_e32 v107, v43
	v_mov_b32_e32 v101, v41
	v_mov_b32_e32 v81, v40
	s_waitcnt vmcnt(35)
; __device__ __forceinline__ void ln_stats(const v4f (&v)[16], float& mean, float& rstd) {
;     float s = 0.f;
; #pragma unroll
;     for (int j = 0; j < 16; ++j) s += (v[j].x + v[j].y) + (v[j].z + v[j].w);
;     mean = wave_sum(s) * (1.f / D_MODEL); float s2 = 0.f;
; #pragma unroll
;     for (int j = 0; j < 16; ++j) { const v4f d = v[j] - mean; s2 += (d.x * d.x + d.y * d.y) + (d.z * d.z + d.w * d.w); }
;     rstd = 1.0f / sqrtf(wave_sum(s2) * (1.f / D_MODEL) + LN_EPS);
	v_mov_b32_e32 v108, v37
	v_mov_b32_e32 v109, v38
	v_mov_b32_e32 v110, v36
	v_mov_b32_e32 v111, v39
	v_pk_add_f32 v[102:103], v[102:103], v[106:107]
	v_pk_add_f32 v[80:81], v[80:81], v[100:101]
	v_pk_add_f32 v[104:105], v[108:109], v[110:111]
	v_pk_add_f32 v[80:81], v[80:81], v[102:103]
	v_pk_add_f32 v[104:105], v[104:105], v[104:105] op_sel:[0,1] op_sel_hi:[1,0]
	v_pk_add_f32 v[80:81], v[80:81], v[80:81] op_sel:[0,1] op_sel_hi:[1,0]
	s_waitcnt vmcnt(34)
	v_add_f32_e32 v112, v32, v33
	v_add_f32_e32 v114, v34, v35
	s_waitcnt vmcnt(33)
	v_mov_b32_e32 v113, v30
	v_mov_b32_e32 v115, v31
	v_mov_b32_e32 v105, v29
	v_mov_b32_e32 v81, v28
	s_waitcnt vmcnt(32)
	v_mov_b32_e32 v106, v25
	v_mov_b32_e32 v107, v26
	v_mov_b32_e32 v108, v24
	v_mov_b32_e32 v109, v27
	v_pk_add_f32 v[96:97], v[112:113], v[114:115]
	v_pk_add_f32 v[80:81], v[80:81], v[104:105]
	v_pk_add_f32 v[106:107], v[106:107], v[108:109]
	v_pk_add_f32 v[80:81], v[80:81], v[96:97]
	v_pk_add_f32 v[106:107], v[106:107], v[106:107] op_sel:[0,1] op_sel_hi:[1,0]
	v_pk_add_f32 v[80:81], v[80:81], v[80:81] op_sel:[0,1] op_sel_hi:[1,0]
	s_waitcnt vmcnt(31)
	v_add_f32_e32 v110, v20, v21
	s_waitcnt vmcnt(30)
	v_mov_b32_e32 v111, v18
	v_add_f32_e32 v116, v22, v23
	v_mov_b32_e32 v117, v19
	v_mov_b32_e32 v107, v17
	v_mov_b32_e32 v81, v16
	v_pk_add_f32 v[108:109], v[110:111], v[116:117]
	v_pk_add_f32 v[80:81], v[80:81], v[106:107]
	s_waitcnt vmcnt(29)
	v_pk_add_f32 v[90:91], v[90:91], 1.0 op_sel_hi:[1,0]
	v_pk_add_f32 v[80:81], v[80:81], v[108:109]
	v_pk_add_f32 v[92:93], v[92:93], 1.0 op_sel_hi:[1,0]
	v_add_f32_e32 v80, v80, v81
	ds_bpermute_b32 v81, v82, v80
	s_waitcnt lgkmcnt(0)
	v_add_f32_e32 v80, v80, v81
	ds_bpermute_b32 v81, v83, v80
	s_waitcnt lgkmcnt(0)
	v_add_f32_e32 v80, v80, v81
	ds_bpermute_b32 v81, v84, v80
	s_waitcnt lgkmcnt(0)
	v_add_f32_e32 v80, v80, v81
	ds_bpermute_b32 v81, v85, v80
	s_waitcnt lgkmcnt(0)
	v_add_f32_e32 v80, v80, v81
	ds_bpermute_b32 v81, v86, v80
	s_waitcnt lgkmcnt(0)
	v_add_f32_e32 v80, v80, v81
	ds_bpermute_b32 v81, v87, v80
	s_waitcnt lgkmcnt(0)
	v_add_f32_e32 v100, v80, v81
	v_fmamk_f32 v95, v100, 0xb9800000, v13
	v_fmamk_f32 v94, v100, 0xb9800000, v12
	v_fmamk_f32 v15, v100, 0xb9800000, v15
	v_fmac_f32_e32 v14, 0xb9800000, v100
	v_fmamk_f32 v97, v100, 0xb9800000, v9
	v_fmamk_f32 v96, v100, 0xb9800000, v8
	v_fmamk_f32 v11, v100, 0xb9800000, v11
	v_fmac_f32_e32 v10, 0xb9800000, v100
	v_fmamk_f32 v9, v100, 0xb9800000, v25
	v_fmamk_f32 v8, v100, 0xb9800000, v24
	v_fmamk_f32 v99, v100, 0xb9800000, v5
	v_fmamk_f32 v98, v100, 0xb9800000, v4
	v_fmamk_f32 v25, v100, 0xb9800000, v45
	v_fmamk_f32 v24, v100, 0xb9800000, v44
	v_fmamk_f32 v13, v100, 0xb9800000, v33
	v_fmamk_f32 v12, v100, 0xb9800000, v32
	v_fmamk_f32 v5, v100, 0xb9800000, v21
	v_fmamk_f32 v4, v100, 0xb9800000, v20
	v_fmamk_f32 v81, v100, 0xb9800000, v3
	v_fmamk_f32 v80, v100, 0xb9800000, v2
	v_fmamk_f32 v45, v100, 0xb9800000, v55
	v_fmamk_f32 v44, v100, 0xb9800000, v54
	v_fmamk_f32 v33, v100, 0xb9800000, v43
	v_fmamk_f32 v32, v100, 0xb9800000, v42
	v_fmamk_f32 v21, v100, 0xb9800000, v31
	v_fmamk_f32 v20, v100, 0xb9800000, v30
	v_fmamk_f32 v3, v100, 0xb9800000, v19
	v_fmamk_f32 v2, v100, 0xb9800000, v18
	v_pk_mul_f32 v[18:19], v[14:15], v[14:15]
	v_pk_mul_f32 v[30:31], v[94:95], v[94:95]
	v_pk_mul_f32 v[42:43], v[10:11], v[10:11]
	v_pk_mul_f32 v[54:55], v[96:97], v[96:97]
	v_fmamk_f32 v61, v100, 0xb9800000, v61
	v_fmamk_f32 v60, v100, 0xb9800000, v60
	v_fmamk_f32 v63, v100, 0xb9800000, v63
	v_fmac_f32_e32 v62, 0xb9800000, v100
	v_fmamk_f32 v49, v100, 0xb9800000, v49
	v_fmamk_f32 v48, v100, 0xb9800000, v48
	v_fmamk_f32 v51, v100, 0xb9800000, v51
	v_fmac_f32_e32 v50, 0xb9800000, v100
	v_fmamk_f32 v37, v100, 0xb9800000, v37
	v_fmamk_f32 v36, v100, 0xb9800000, v36
	v_fmamk_f32 v39, v100, 0xb9800000, v39
	v_fmac_f32_e32 v38, 0xb9800000, v100
	v_fmamk_f32 v27, v100, 0xb9800000, v27
	v_fmac_f32_e32 v26, 0xb9800000, v100
	v_fmac_f32_e32 v6, 0xb9800000, v100
	v_pk_mov_b32 v[136:137], v[30:31], v[18:19] op_sel:[1,0]
	v_mov_b32_e32 v31, v19
	v_pk_mov_b32 v[18:19], v[54:55], v[42:43] op_sel:[1,0]
	v_mov_b32_e32 v55, v43
	v_fmamk_f32 v7, v100, 0xb9800000, v7
	v_fmamk_f32 v1, v100, 0xb9800000, v1
	v_fmac_f32_e32 v0, 0xb9800000, v100
	v_fmamk_f32 v57, v100, 0xb9800000, v57
	v_fmamk_f32 v56, v100, 0xb9800000, v56
	v_fmamk_f32 v59, v100, 0xb9800000, v59
	v_fmac_f32_e32 v58, 0xb9800000, v100
	v_fmamk_f32 v53, v100, 0xb9800000, v53
	v_fmac_f32_e32 v52, 0xb9800000, v100
	v_fmamk_f32 v47, v100, 0xb9800000, v47
	v_fmac_f32_e32 v46, 0xb9800000, v100
	v_fmamk_f32 v41, v100, 0xb9800000, v41
	v_fmac_f32_e32 v40, 0xb9800000, v100
	v_fmamk_f32 v35, v100, 0xb9800000, v35
	v_fmac_f32_e32 v34, 0xb9800000, v100
	v_fmamk_f32 v29, v100, 0xb9800000, v29
	v_fmac_f32_e32 v28, 0xb9800000, v100
	v_fmamk_f32 v23, v100, 0xb9800000, v23
	v_fmac_f32_e32 v22, 0xb9800000, v100
	v_fmamk_f32 v17, v100, 0xb9800000, v17
	v_fmac_f32_e32 v16, 0xb9800000, v100
	v_pk_mul_f32 v[100:101], v[62:63], v[62:63]
	v_pk_mul_f32 v[102:103], v[60:61], v[60:61]
	v_pk_mul_f32 v[104:105], v[50:51], v[50:51]
	v_pk_mul_f32 v[106:107], v[48:49], v[48:49]
	v_pk_mul_f32 v[108:109], v[38:39], v[38:39]
	v_pk_mul_f32 v[110:111], v[36:37], v[36:37]
	v_pk_mul_f32 v[112:113], v[26:27], v[26:27]
	v_pk_mul_f32 v[114:115], v[8:9], v[8:9]
	v_mul_f32_e32 v116, v98, v98
	v_mul_f32_e32 v118, v6, v6
	v_pk_add_f32 v[30:31], v[136:137], v[30:31]
	v_pk_add_f32 v[18:19], v[18:19], v[54:55]
	v_pk_mov_b32 v[42:43], v[102:103], v[100:101] op_sel:[1,0]
	v_mov_b32_e32 v103, v101
	v_pk_mov_b32 v[100:101], v[106:107], v[104:105] op_sel:[1,0]
	v_mov_b32_e32 v107, v105
	v_pk_mov_b32 v[104:105], v[110:111], v[108:109] op_sel:[1,0]
; __device__ __forceinline__ unsigned pkbf(float lo, float hi) { unsigned r; asm volatile("v_cvt_pk_bf16_f32 %0, %1, %2" : "=v"(r) : "v"(lo), "v"(hi)); return r; }
; __device__ __forceinline__ void ln_stats(const v4f (&v)[16], float& mean, float& rstd) {
;     ...
;     for (int j = 0; j < 16; ++j) { const v4f d = v[j] - mean; s2 += (d.x * d.x + d.y * d.y) + (d.z * d.z + d.w * d.w); }
;     rstd = 1.0f / sqrtf(wave_sum(s2) * (1.f / D_MODEL) + LN_EPS);
; }
; __device__ __forceinline__ void phase_h(const Ctx& X, const float* x, const float* mod, bf16* h) {
;     ...
;         for (int j = 0; j < 16; ++j) { const v4f y = (v[j] - mean) * rstd * (sc[64 * j] + 1.0f) + sh[64 * j]; v2u w; w.x = pkbf(y.x, y.y); w.y = pkbf(y.z, y.w); o[64 * j] = w; }
	v_mov_b32_e32 v111, v109
	v_pk_mov_b32 v[108:109], v[114:115], v[112:113] op_sel:[1,0]
	v_mov_b32_e32 v115, v113
	v_pk_fma_f32 v[112:113], v[98:99], v[98:99], v[116:117] op_sel_hi:[1,1,0]
	v_pk_fma_f32 v[116:117], v[6:7], v[6:7], v[118:119] op_sel_hi:[1,1,0]
	v_pk_add_f32 v[30:31], v[30:31], v[30:31] op_sel_hi:[0,1]
	v_pk_add_f32 v[18:19], v[18:19], v[18:19] op_sel_hi:[0,1]
	v_mul_f32_e32 v112, v0, v0
	v_mul_f32_e32 v116, v1, v1
	v_mul_f32_e32 v30, v80, v80
	v_mul_f32_e32 v18, v81, v81
	v_pk_add_f32 v[54:55], v[100:101], v[106:107]
	v_pk_add_f32 v[100:101], v[104:105], v[110:111]
	v_pk_add_f32 v[104:105], v[112:113], v[116:117]
	v_pk_add_f32 v[18:19], v[30:31], v[18:19]
	v_mul_f32_e32 v120, v56, v56
	v_mul_f32_e32 v122, v58, v58
	v_pk_add_f32 v[42:43], v[42:43], v[102:103]
	v_pk_add_f32 v[18:19], v[104:105], v[18:19]
	v_pk_fma_f32 v[118:119], v[56:57], v[56:57], v[120:121] op_sel_hi:[1,1,0]
	v_pk_fma_f32 v[120:121], v[58:59], v[58:59], v[122:123] op_sel_hi:[1,1,0]
	v_pk_add_f32 v[42:43], v[42:43], v[42:43] op_sel_hi:[0,1]
	v_pk_add_f32 v[18:19], v[18:19], v[18:19] op_sel_hi:[0,1]
	v_mul_f32_e32 v118, v52, v52
	v_mul_f32_e32 v120, v53, v53
	v_mul_f32_e32 v42, v44, v44
	v_mul_f32_e32 v18, v45, v45
	v_pk_add_f32 v[106:107], v[118:119], v[120:121]
	v_pk_add_f32 v[18:19], v[42:43], v[18:19]
	v_mul_f32_e32 v124, v24, v24
	v_mul_f32_e32 v126, v46, v46
	v_pk_add_f32 v[18:19], v[106:107], v[18:19]
	v_pk_fma_f32 v[122:123], v[24:25], v[24:25], v[124:125] op_sel_hi:[1,1,0]
	v_pk_fma_f32 v[124:125], v[46:47], v[46:47], v[126:127] op_sel_hi:[1,1,0]
	v_pk_add_f32 v[54:55], v[54:55], v[54:55] op_sel_hi:[0,1]
	v_pk_add_f32 v[18:19], v[18:19], v[18:19] op_sel_hi:[0,1]
	v_mul_f32_e32 v122, v40, v40
	v_mul_f32_e32 v124, v41, v41
	v_mul_f32_e32 v54, v32, v32
	v_mul_f32_e32 v18, v33, v33
	v_pk_add_f32 v[102:103], v[108:109], v[114:115]
	v_pk_add_f32 v[108:109], v[122:123], v[124:125]
	v_pk_add_f32 v[18:19], v[54:55], v[18:19]
	v_mul_f32_e32 v128, v12, v12
	v_mul_f32_e32 v130, v34, v34
	v_pk_add_f32 v[18:19], v[108:109], v[18:19]
	v_pk_fma_f32 v[126:127], v[12:13], v[12:13], v[128:129] op_sel_hi:[1,1,0]
	v_pk_fma_f32 v[128:129], v[34:35], v[34:35], v[130:131] op_sel_hi:[1,1,0]
	v_pk_add_f32 v[100:101], v[100:101], v[100:101] op_sel_hi:[0,1]
	v_pk_add_f32 v[18:19], v[18:19], v[18:19] op_sel_hi:[0,1]
	v_mul_f32_e32 v126, v28, v28
	v_mul_f32_e32 v128, v29, v29
	v_mul_f32_e32 v100, v20, v20
	v_mul_f32_e32 v18, v21, v21
	v_pk_add_f32 v[110:111], v[126:127], v[128:129]
	v_pk_add_f32 v[18:19], v[100:101], v[18:19]
	v_mul_f32_e32 v132, v4, v4
	v_mul_f32_e32 v134, v22, v22
	v_pk_add_f32 v[18:19], v[110:111], v[18:19]
	v_pk_fma_f32 v[130:131], v[4:5], v[4:5], v[132:133] op_sel_hi:[1,1,0]
	v_pk_fma_f32 v[132:133], v[22:23], v[22:23], v[134:135] op_sel_hi:[1,1,0]
	v_pk_add_f32 v[102:103], v[102:103], v[102:103] op_sel_hi:[0,1]
	v_pk_add_f32 v[18:19], v[18:19], v[18:19] op_sel_hi:[0,1]
	v_mul_f32_e32 v130, v16, v16
	v_mul_f32_e32 v132, v17, v17
	v_mul_f32_e32 v102, v2, v2
	v_mul_f32_e32 v18, v3, v3
	v_pk_add_f32 v[112:113], v[130:131], v[132:133]
	v_pk_add_f32 v[18:19], v[102:103], v[18:19]
	s_nop 0
	v_pk_add_f32 v[18:19], v[112:113], v[18:19]
	s_nop 0
	v_add_f32_e32 v18, v18, v19
	ds_bpermute_b32 v19, v82, v18
	s_waitcnt lgkmcnt(0)
	v_add_f32_e32 v18, v18, v19
	ds_bpermute_b32 v19, v83, v18
	s_waitcnt lgkmcnt(0)
	v_add_f32_e32 v18, v18, v19
	ds_bpermute_b32 v19, v84, v18
	s_waitcnt lgkmcnt(0)
	v_add_f32_e32 v18, v18, v19
	ds_bpermute_b32 v19, v85, v18
	s_waitcnt lgkmcnt(0)
	v_add_f32_e32 v18, v18, v19
	ds_bpermute_b32 v19, v86, v18
	s_waitcnt lgkmcnt(0)
	v_add_f32_e32 v18, v18, v19
	ds_bpermute_b32 v19, v87, v18
	s_waitcnt lgkmcnt(0)
	v_add_f32_e32 v18, v18, v19
	v_fmamk_f32 v18, v18, 0x39800000, v88
	v_mul_f32_e32 v19, 0x4f800000, v18
	v_cmp_gt_f32_e32 vcc, s19, v18
	s_nop 1
	v_cndmask_b32_e32 v18, v18, v19, vcc
	v_sqrt_f32_e32 v19, v18
	s_nop 0
	v_add_u32_e32 v30, -1, v19
	v_add_u32_e32 v31, 1, v19
	v_fma_f32 v42, -v30, v19, v18
	v_fma_f32 v43, -v31, v19, v18
	v_cmp_ge_f32_e64 s[2:3], 0, v42
	s_nop 1
	v_cndmask_b32_e64 v19, v19, v30, s[2:3]
	v_cmp_lt_f32_e64 s[2:3], 0, v43
	s_nop 1
	v_cndmask_b32_e64 v19, v19, v31, s[2:3]
	v_mul_f32_e32 v30, 0x37800000, v19
	v_cndmask_b32_e32 v19, v19, v30, vcc
	v_cmp_class_f32_e32 vcc, v18, v89
	s_nop 1
	v_cndmask_b32_e32 v18, v19, v18, vcc
	v_div_scale_f32 v19, s[2:3], v18, v18, 1.0
	v_rcp_f32_e32 v31, v19
	v_div_scale_f32 v30, vcc, 1.0, v18, 1.0
	v_fma_f32 v42, -v19, v31, 1.0
	v_fmac_f32_e32 v31, v42, v31
	v_mul_f32_e32 v42, v30, v31
	v_fma_f32 v43, -v19, v42, v30
	v_fmac_f32_e32 v42, v43, v31
	v_fma_f32 v19, -v19, v42, v30
	v_div_fmas_f32 v19, v19, v31, v42
	v_div_fixup_f32 v18, v19, v18, 1.0
	v_pk_mul_f32 v[30:31], v[94:95], v[18:19] op_sel_hi:[1,0]
	v_pk_mul_f32 v[14:15], v[14:15], v[18:19] op_sel_hi:[1,0]
	s_waitcnt vmcnt(0)
; #define GAS __attribute__((address_space(1)))
; __device__ __forceinline__ unsigned pkbf(float lo, float hi) { unsigned r; asm volatile("v_cvt_pk_bf16_f32 %0, %1, %2" : "=v"(r) : "v"(lo), "v"(hi)); return r; }
; __device__ __forceinline__ void phase_h(const Ctx& X, const float* x, const float* mod, bf16* h) {
;     ...
;         const GAS v4f* sh = (const GAS v4f*)(mrow) + X.lane; const GAS v4f* sc = (const GAS v4f*)(mrow + D_MODEL) + X.lane;
;         GAS v2u* o = (GAS v2u*)(h + (size_t)m * D_MODEL) + X.lane;
; #pragma unroll
;         for (int j = 0; j < 16; ++j) { const v4f y = (v[j] - mean) * rstd * (sc[64 * j] + 1.0f) + sh[64 * j]; v2u w; w.x = pkbf(y.x, y.y); w.y = pkbf(y.z, y.w); o[64 * j] = w; }
	v_pk_fma_f32 v[30:31], v[90:91], v[30:31], v[64:65]
	v_pk_fma_f32 v[14:15], v[92:93], v[14:15], v[66:67]
	v_cvt_pk_bf16_f32 v30, v30, v31
	v_pk_mul_f32 v[10:11], v[10:11], v[18:19] op_sel_hi:[1,0]
	v_cvt_pk_bf16_f32 v31, v14, v15
	global_store_dwordx2 v[70:71], v[30:31], off
	v_pk_mul_f32 v[14:15], v[96:97], v[18:19] op_sel_hi:[1,0]
	v_pk_mul_f32 v[6:7], v[6:7], v[18:19] op_sel_hi:[1,0]
	v_pk_mul_f32 v[0:1], v[0:1], v[18:19] op_sel_hi:[1,0]
	v_pk_mul_f32 v[24:25], v[24:25], v[18:19] op_sel_hi:[1,0]
	v_pk_mul_f32 v[36:37], v[36:37], v[18:19] op_sel_hi:[1,0]
	v_pk_mul_f32 v[20:21], v[20:21], v[18:19] op_sel_hi:[1,0]
	v_pk_mul_f32 v[4:5], v[4:5], v[18:19] op_sel_hi:[1,0]
	v_pk_mul_f32 v[2:3], v[2:3], v[18:19] op_sel_hi:[1,0]
	v_pk_add_f32 v[42:43], v[138:139], 1.0 op_sel_hi:[1,0]
	v_pk_add_f32 v[30:31], v[140:141], 1.0 op_sel_hi:[1,0]
	v_pk_fma_f32 v[14:15], v[42:43], v[14:15], v[142:143]
	v_pk_fma_f32 v[10:11], v[30:31], v[10:11], v[144:145]
	v_cvt_pk_bf16_f32 v14, v14, v15
	s_nop 0
	v_cvt_pk_bf16_f32 v15, v10, v11
	global_store_dwordx2 v[70:71], v[14:15], off offset:512
	v_pk_mul_f32 v[10:11], v[98:99], v[18:19] op_sel_hi:[1,0]
	v_pk_add_f32 v[30:31], v[146:147], 1.0 op_sel_hi:[1,0]
	v_pk_add_f32 v[14:15], v[148:149], 1.0 op_sel_hi:[1,0]
	v_pk_fma_f32 v[10:11], v[30:31], v[10:11], v[150:151]
	v_pk_fma_f32 v[6:7], v[14:15], v[6:7], v[152:153]
	v_cvt_pk_bf16_f32 v10, v10, v11
	s_nop 0
	v_cvt_pk_bf16_f32 v11, v6, v7
	global_store_dwordx2 v[70:71], v[10:11], off offset:1024
	v_pk_mul_f32 v[10:11], v[80:81], v[18:19] op_sel_hi:[1,0]
	v_add_co_u32_e32 v6, vcc, s7, v74
	v_pk_add_f32 v[30:31], v[154:155], 1.0 op_sel_hi:[1,0]
	v_pk_add_f32 v[14:15], v[156:157], 1.0 op_sel_hi:[1,0]
	v_pk_fma_f32 v[0:1], v[30:31], v[0:1], v[158:159]
	v_pk_fma_f32 v[10:11], v[14:15], v[10:11], v[160:161]
	v_cvt_pk_bf16_f32 v0, v0, v1
	v_addc_co_u32_e32 v7, vcc, 0, v75, vcc
	v_cvt_pk_bf16_f32 v1, v10, v11
	global_store_dwordx2 v[70:71], v[0:1], off offset:1536
	v_pk_mul_f32 v[14:15], v[60:61], v[18:19] op_sel_hi:[1,0]
	v_pk_mul_f32 v[10:11], v[62:63], v[18:19] op_sel_hi:[1,0]
	v_add_co_u32_e32 v0, vcc, s5, v74
	v_pk_add_f32 v[42:43], v[162:163], 1.0 op_sel_hi:[1,0]
	v_pk_add_f32 v[30:31], v[164:165], 1.0 op_sel_hi:[1,0]
	v_pk_fma_f32 v[14:15], v[42:43], v[14:15], v[166:167]
	v_pk_fma_f32 v[10:11], v[30:31], v[10:11], v[168:169]
	v_cvt_pk_bf16_f32 v14, v14, v15
	v_addc_co_u32_e32 v1, vcc, 0, v75, vcc
	v_cvt_pk_bf16_f32 v15, v10, v11
	global_store_dwordx2 v[70:71], v[14:15], off offset:2048
	v_pk_mul_f32 v[14:15], v[56:57], v[18:19] op_sel_hi:[1,0]
	v_pk_mul_f32 v[10:11], v[58:59], v[18:19] op_sel_hi:[1,0]
	v_pk_add_f32 v[42:43], v[170:171], 1.0 op_sel_hi:[1,0]
	v_pk_add_f32 v[30:31], v[172:173], 1.0 op_sel_hi:[1,0]
	v_pk_fma_f32 v[14:15], v[42:43], v[14:15], v[174:175]
	v_pk_fma_f32 v[10:11], v[30:31], v[10:11], v[176:177]
	v_cvt_pk_bf16_f32 v14, v14, v15
	s_nop 0
	v_cvt_pk_bf16_f32 v15, v10, v11
	global_store_dwordx2 v[70:71], v[14:15], off offset:2560
	v_pk_mul_f32 v[10:11], v[52:53], v[18:19] op_sel_hi:[1,0]
	v_pk_mul_f32 v[14:15], v[44:45], v[18:19] op_sel_hi:[1,0]
	v_pk_add_f32 v[42:43], v[178:179], 1.0 op_sel_hi:[1,0]
	v_pk_add_f32 v[30:31], v[180:181], 1.0 op_sel_hi:[1,0]
	v_pk_fma_f32 v[10:11], v[42:43], v[10:11], v[182:183]
	v_pk_fma_f32 v[14:15], v[30:31], v[14:15], v[184:185]
	v_cvt_pk_bf16_f32 v10, v10, v11
	s_nop 0
	v_cvt_pk_bf16_f32 v11, v14, v15
	global_store_dwordx2 v[70:71], v[10:11], off offset:3072
	v_pk_mul_f32 v[14:15], v[48:49], v[18:19] op_sel_hi:[1,0]
	v_add_co_u32_e32 v0, vcc, s22, v74
	v_pk_mul_f32 v[10:11], v[50:51], v[18:19] op_sel_hi:[1,0]
	s_nop 0
	v_addc_co_u32_e32 v1, vcc, 0, v75, vcc
	v_pk_add_f32 v[42:43], v[186:187], 1.0 op_sel_hi:[1,0]
	v_pk_add_f32 v[30:31], v[188:189], 1.0 op_sel_hi:[1,0]
	v_pk_fma_f32 v[14:15], v[14:15], v[42:43], v[190:191]
	v_pk_fma_f32 v[10:11], v[10:11], v[30:31], v[192:193]
	v_cvt_pk_bf16_f32 v14, v14, v15
; #define GAS __attribute__((address_space(1)))
; __device__ __forceinline__ unsigned pkbf(float lo, float hi) { unsigned r; asm volatile("v_cvt_pk_bf16_f32 %0, %1, %2" : "=v"(r) : "v"(lo), "v"(hi)); return r; }
; __device__ __forceinline__ void phase_h(const Ctx& X, const float* x, const float* mod, bf16* h) {
;     ...
;         const GAS v4f* sh = (const GAS v4f*)(mrow) + X.lane; const GAS v4f* sc = (const GAS v4f*)(mrow + D_MODEL) + X.lane;
;         GAS v2u* o = (GAS v2u*)(h + (size_t)m * D_MODEL) + X.lane;
; #pragma unroll
;         for (int j = 0; j < 16; ++j) { const v4f y = (v[j] - mean) * rstd * (sc[64 * j] + 1.0f) + sh[64 * j]; v2u w; w.x = pkbf(y.x, y.y); w.y = pkbf(y.z, y.w); o[64 * j] = w; }
	v_pk_mul_f32 v[30:31], v[46:47], v[18:19] op_sel_hi:[1,0]
	v_cvt_pk_bf16_f32 v15, v10, v11
	global_store_dwordx2 v[70:71], v[14:15], off offset:3584
	v_add_co_u32_e32 v14, vcc, s5, v70
	v_pk_add_f32 v[42:43], v[194:195], 1.0 op_sel_hi:[1,0]
	v_addc_co_u32_e32 v15, vcc, 0, v71, vcc
	v_add_co_u32_e32 v10, vcc, s21, v74
	v_pk_add_f32 v[44:45], v[196:197], 1.0 op_sel_hi:[1,0]
	v_pk_fma_f32 v[24:25], v[24:25], v[42:43], v[198:199]
	v_addc_co_u32_e32 v11, vcc, 0, v75, vcc
	v_pk_fma_f32 v[30:31], v[30:31], v[44:45], v[200:201]
	v_cvt_pk_bf16_f32 v24, v24, v25
	v_lshl_add_u64 v[70:71], v[70:71], 0, s[8:9]
	v_cvt_pk_bf16_f32 v25, v30, v31
	global_store_dwordx2 v[14:15], v[24:25], off
	v_pk_mul_f32 v[24:25], v[40:41], v[18:19] op_sel_hi:[1,0]
	v_pk_mul_f32 v[30:31], v[32:33], v[18:19] op_sel_hi:[1,0]
	v_pk_add_f32 v[40:41], v[202:203], 1.0 op_sel_hi:[1,0]
	v_pk_add_f32 v[32:33], v[204:205], 1.0 op_sel_hi:[1,0]
	v_pk_fma_f32 v[24:25], v[24:25], v[40:41], v[206:207]
	v_pk_fma_f32 v[30:31], v[30:31], v[32:33], v[208:209]
	v_cvt_pk_bf16_f32 v24, v24, v25
	s_nop 0
	v_cvt_pk_bf16_f32 v25, v30, v31
	global_store_dwordx2 v[14:15], v[24:25], off offset:512
	v_pk_mul_f32 v[24:25], v[38:39], v[18:19] op_sel_hi:[1,0]
	v_pk_add_f32 v[30:31], v[210:211], 1.0 op_sel_hi:[1,0]
	v_pk_add_f32 v[32:33], v[212:213], 1.0 op_sel_hi:[1,0]
	v_pk_fma_f32 v[30:31], v[36:37], v[30:31], v[214:215]
	v_pk_fma_f32 v[24:25], v[24:25], v[32:33], v[216:217]
	v_cvt_pk_bf16_f32 v30, v30, v31
	s_nop 0
	v_cvt_pk_bf16_f32 v31, v24, v25
	global_store_dwordx2 v[14:15], v[30:31], off offset:1024
	s_nop 0
	v_pk_mul_f32 v[6:7], v[12:13], v[18:19] op_sel_hi:[1,0]
	v_pk_mul_f32 v[10:11], v[34:35], v[18:19] op_sel_hi:[1,0]
	v_add_co_u32_e32 v24, vcc, s18, v74
	v_pk_add_f32 v[30:31], v[218:219], 1.0 op_sel_hi:[1,0]
	v_pk_add_f32 v[12:13], v[220:221], 1.0 op_sel_hi:[1,0]
	v_pk_fma_f32 v[6:7], v[6:7], v[30:31], v[222:223]
	v_pk_fma_f32 v[10:11], v[10:11], v[12:13], v[224:225]
	v_cvt_pk_bf16_f32 v6, v6, v7
	v_addc_co_u32_e32 v25, vcc, 0, v75, vcc
	v_cvt_pk_bf16_f32 v7, v10, v11
	global_store_dwordx2 v[14:15], v[6:7], off offset:1536
	v_pk_mul_f32 v[6:7], v[28:29], v[18:19] op_sel_hi:[1,0]
	v_pk_add_f32 v[10:11], v[226:227], 1.0 op_sel_hi:[1,0]
	v_pk_add_f32 v[12:13], v[228:229], 1.0 op_sel_hi:[1,0]
	v_pk_fma_f32 v[6:7], v[6:7], v[10:11], v[230:231]
	v_pk_fma_f32 v[12:13], v[20:21], v[12:13], v[232:233]
	v_cvt_pk_bf16_f32 v6, v6, v7
	v_pk_mul_f32 v[20:21], v[22:23], v[18:19] op_sel_hi:[1,0]
	v_cvt_pk_bf16_f32 v7, v12, v13
	global_store_dwordx2 v[14:15], v[6:7], off offset:2048
	v_pk_mul_f32 v[6:7], v[8:9], v[18:19] op_sel_hi:[1,0]
	v_pk_mul_f32 v[8:9], v[26:27], v[18:19] op_sel_hi:[1,0]
	v_pk_add_f32 v[10:11], v[234:235], 1.0 op_sel_hi:[1,0]
	v_pk_add_f32 v[12:13], v[236:237], 1.0 op_sel_hi:[1,0]
	v_pk_fma_f32 v[6:7], v[6:7], v[10:11], v[238:239]
	v_pk_fma_f32 v[8:9], v[8:9], v[12:13], v[240:241]
	v_cvt_pk_bf16_f32 v6, v6, v7
	s_nop 0
	v_cvt_pk_bf16_f32 v7, v8, v9
	global_store_dwordx2 v[14:15], v[6:7], off offset:2560
	s_nop 0
	v_pk_add_f32 v[6:7], v[242:243], 1.0 op_sel_hi:[1,0]
	v_pk_add_f32 v[8:9], v[244:245], 1.0 op_sel_hi:[1,0]
	v_pk_fma_f32 v[4:5], v[4:5], v[6:7], v[246:247]
	v_pk_fma_f32 v[8:9], v[20:21], v[8:9], v[248:249]
	v_cvt_pk_bf16_f32 v4, v4, v5
	s_nop 0
	v_cvt_pk_bf16_f32 v5, v8, v9
	global_store_dwordx2 v[14:15], v[4:5], off offset:3072
	global_load_dwordx4 v[4:7], v[0:1], off offset:3072
	s_nop 0
	global_load_dwordx4 v[8:11], v[24:25], off offset:3072
	v_pk_mul_f32 v[0:1], v[16:17], v[18:19] op_sel_hi:[1,0]
	s_waitcnt vmcnt(1)
	v_pk_add_f32 v[4:5], v[4:5], 1.0 op_sel_hi:[1,0]
	v_pk_add_f32 v[6:7], v[6:7], 1.0 op_sel_hi:[1,0]
	s_waitcnt vmcnt(0)
	v_pk_fma_f32 v[0:1], v[0:1], v[4:5], v[8:9]
	v_pk_fma_f32 v[2:3], v[2:3], v[6:7], v[10:11]
	v_cvt_pk_bf16_f32 v0, v0, v1
	s_nop 0
	v_cvt_pk_bf16_f32 v1, v2, v3
	global_store_dwordx2 v[14:15], v[0:1], off offset:3584
	s_cbranch_scc1 .LBB0_91

; #define GAS __attribute__((address_space(1)))
; __device__ __forceinline__ void phase_ln1(const Ctx& X, const float* r1, const float* g, const float* bt, const float* mod, float* stats, bf16* h2) {
;     ...
;         for (int j = 0; j < 16; ++j) v[j] = rr[64 * j];
;         float mean, rstd; ln_stats(v, mean, rstd);
;         const float* gl = g; const float* bl = bt; asm volatile("" : "+s"(gl), "+s"(bl));
;         const GAS v4f* gp = (const GAS v4f*)gl + X.lane; const GAS v4f* bp = (const GAS v4f*)bl + X.lane;
;         if (X.lane == 0) { typedef float f2_ __attribute__((ext_vector_type(2))); *(GAS f2_*)(stats + 2 * (size_t)m) = (f2_){mean, rstd}; }
; #pragma unroll
;         for (int j = 0; j < 16; ++j) { v[j] = (v[j] - mean) * rstd * gp[64 * j] + bp[64 * j]; if ((j & 3) == 3) asm volatile("" ::: "memory"); }
;         ln_stats(v, mean, rstd);
;         const float* mrow = mod + (size_t)(m / SEQ) * MOD_LD;
;         const GAS v4f* sh = (const GAS v4f*)(mrow + 3 * D_MODEL) + X.lane; const GAS v4f* sc = (const GAS v4f*)(mrow + 4 * D_MODEL) + X.lane;
.LBB0_1095:
	s_or_b64 exec, exec, s[22:23]
	v_lshl_add_u64 v[18:19], s[4:5], 0, v[64:65]
	v_add_co_u32_e32 v70, vcc, s9, v18
	v_lshl_add_u64 v[34:35], s[20:21], 0, v[64:65]
	s_nop 0
	v_addc_co_u32_e32 v71, vcc, 0, v19, vcc
	v_add_co_u32_e32 v178, vcc, s28, v18
	global_load_dwordx4 v[86:89], v64, s[20:21]
	global_load_dwordx4 v[90:93], v64, s[20:21] offset:1024
	global_load_dwordx4 v[94:97], v64, s[4:5]
	global_load_dwordx4 v[98:101], v64, s[4:5] offset:1024
	global_load_dwordx4 v[102:105], v64, s[20:21] offset:2048
	global_load_dwordx4 v[106:109], v64, s[20:21] offset:3072
	global_load_dwordx4 v[110:113], v64, s[4:5] offset:2048
	global_load_dwordx4 v[114:117], v64, s[4:5] offset:3072
	v_addc_co_u32_e32 v179, vcc, 0, v19, vcc
	v_add_co_u32_e32 v142, vcc, s9, v34
	global_load_dwordx4 v[118:121], v[178:179], off offset:-4096
	s_nop 0
	v_addc_co_u32_e32 v143, vcc, 0, v35, vcc
	v_add_co_u32_e32 v170, vcc, s28, v34
	v_pk_mul_f32 v[214:215], v[62:63], v[76:77] op_sel_hi:[1,0]
	s_nop 0
	v_addc_co_u32_e32 v171, vcc, 0, v35, vcc
	global_load_dwordx4 v[122:125], v[170:171], off offset:-4096
	global_load_dwordx4 v[126:129], v[70:71], off offset:1024
	global_load_dwordx4 v[130:133], v[142:143], off offset:1024
	global_load_dwordx4 v[134:137], v[142:143], off offset:2048
	global_load_dwordx4 v[138:141], v[70:71], off offset:2048
	s_nop 0
	global_load_dwordx4 v[142:145], v[142:143], off offset:3072
	s_nop 0
	global_load_dwordx4 v[146:149], v[70:71], off offset:3072
	v_add_co_u32_e32 v18, vcc, s29, v18
	global_load_dwordx4 v[150:153], v[170:171], off
	global_load_dwordx4 v[154:157], v[170:171], off offset:1024
	global_load_dwordx4 v[158:161], v[178:179], off
	global_load_dwordx4 v[162:165], v[178:179], off offset:1024
	global_load_dwordx4 v[166:169], v[170:171], off offset:2048
	s_nop 0
	global_load_dwordx4 v[170:173], v[170:171], off offset:3072
	s_nop 0
	global_load_dwordx4 v[174:177], v[178:179], off offset:2048
	s_nop 0
	global_load_dwordx4 v[178:181], v[178:179], off offset:3072
	v_addc_co_u32_e32 v19, vcc, 0, v19, vcc
	v_add_co_u32_e32 v34, vcc, s29, v34
	global_load_dwordx4 v[182:185], v[18:19], off
	s_nop 0
	v_addc_co_u32_e32 v35, vcc, 0, v35, vcc
	global_load_dwordx4 v[186:189], v[34:35], off
	global_load_dwordx4 v[190:193], v[34:35], off offset:1024
	global_load_dwordx4 v[194:197], v[18:19], off offset:1024
	global_load_dwordx4 v[198:201], v[18:19], off offset:2048
	global_load_dwordx4 v[202:205], v[34:35], off offset:2048
	global_load_dwordx4 v[206:209], v[34:35], off offset:3072
	global_load_dwordx4 v[210:213], v[18:19], off offset:3072
	v_pk_mul_f32 v[18:19], v[58:59], v[76:77] op_sel_hi:[1,0]
	v_pk_mul_f32 v[34:35], v[56:57], v[76:77] op_sel_hi:[1,0]
	v_pk_mul_f32 v[40:41], v[40:41], v[76:77] op_sel_hi:[1,0]
	v_pk_mul_f32 v[220:221], v[52:53], v[76:77] op_sel_hi:[1,0]
	v_pk_mul_f32 v[14:15], v[14:15], v[76:77] op_sel_hi:[1,0]
	v_pk_mul_f32 v[10:11], v[10:11], v[76:77] op_sel_hi:[1,0]
	v_pk_mul_f32 v[6:7], v[6:7], v[76:77] op_sel_hi:[1,0]
	v_pk_mul_f32 v[50:51], v[50:51], v[76:77] op_sel_hi:[1,0]
	v_pk_mul_f32 v[48:49], v[48:49], v[76:77] op_sel_hi:[1,0]
	v_pk_mul_f32 v[28:29], v[28:29], v[76:77] op_sel_hi:[1,0]
	v_pk_mul_f32 v[2:3], v[2:3], v[76:77] op_sel_hi:[1,0]
	v_pk_mul_f32 v[216:217], v[60:61], v[76:77] op_sel_hi:[1,0]
	v_pk_mul_f32 v[24:25], v[24:25], v[76:77] op_sel_hi:[1,0]
	v_pk_mul_f32 v[20:21], v[20:21], v[76:77] op_sel_hi:[1,0]
	v_pk_mul_f32 v[12:13], v[12:13], v[76:77] op_sel_hi:[1,0]
	v_pk_mul_f32 v[46:47], v[46:47], v[76:77] op_sel_hi:[1,0]
	v_pk_mul_f32 v[44:45], v[44:45], v[76:77] op_sel_hi:[1,0]
	v_pk_mul_f32 v[42:43], v[42:43], v[76:77] op_sel_hi:[1,0]
	v_pk_mul_f32 v[218:219], v[54:55], v[76:77] op_sel_hi:[1,0]
	s_ashr_i32 s4, s6, 31
	s_lshr_b32 s4, s4, 20
	s_add_i32 s4, s6, s4
	s_ashr_i32 s4, s4, 12
	s_mul_hi_i32 s5, s4, 0x18000
	s_mul_i32 s4, s4, 0x18000
	s_add_u32 s4, s24, s4
	s_addc_u32 s5, s25, s5
	s_add_u32 s56, s4, 0x10000
	s_addc_u32 s57, s5, 0
	s_add_u32 s58, s4, 0x11000
	s_addc_u32 s59, s5, 0
	s_add_u32 s60, s4, 0x12000
	s_addc_u32 s61, s5, 0
	s_add_u32 s62, s4, 0x13000
	s_addc_u32 s63, s5, 0
	s_add_u32 s64, s4, 0xc000
	s_addc_u32 s65, s5, 0
	s_add_u32 s66, s4, 0xd000
	s_addc_u32 s67, s5, 0
	s_add_u32 s68, s4, 0xe000
	s_addc_u32 s69, s5, 0
	s_add_u32 s70, s4, 0xf000
	s_addc_u32 s71, s5, 0
	s_add_i32 s6, s6, s8
	s_add_u32 s26, s26, s10
	s_addc_u32 s27, s27, s11
	s_cmpk_lt_i32 s6, 0x4000
	v_lshl_add_u64 v[68:69], v[68:69], 0, s[14:15]
	s_waitcnt vmcnt(29)
	v_pk_fma_f32 v[62:63], v[18:19], v[96:97], v[88:89]
	v_pk_mul_f32 v[18:19], v[38:39], v[76:77] op_sel_hi:[1,0]
	v_pk_fma_f32 v[70:71], v[34:35], v[94:95], v[86:87]
	v_pk_mul_f32 v[34:35], v[36:37], v[76:77] op_sel_hi:[1,0]
	s_waitcnt vmcnt(28)
	v_pk_fma_f32 v[58:59], v[50:51], v[100:101], v[92:93]
	s_waitcnt vmcnt(24)
	v_pk_fma_f32 v[52:53], v[40:41], v[114:115], v[106:107]
	v_pk_fma_f32 v[60:61], v[48:49], v[98:99], v[90:91]
	v_pk_fma_f32 v[54:55], v[46:47], v[112:113], v[104:105]
	v_pk_fma_f32 v[56:57], v[44:45], v[110:111], v[102:103]
	v_pk_fma_f32 v[50:51], v[42:43], v[116:117], v[108:109]
	v_add_f32_e32 v86, v54, v55
	v_mov_b32_e32 v87, v51
	v_lshl_add_u64 v[98:99], s[94:95], 0, v[66:67]
	s_waitcnt vmcnt(22)
	v_pk_fma_f32 v[46:47], v[214:215], v[120:121], v[124:125]
	v_pk_fma_f32 v[48:49], v[216:217], v[118:119], v[122:123]
	s_waitcnt vmcnt(20)
	v_pk_fma_f32 v[42:43], v[218:219], v[128:129], v[132:133]
	v_pk_fma_f32 v[44:45], v[220:221], v[126:127], v[130:131]
	s_waitcnt vmcnt(18)
	v_pk_fma_f32 v[38:39], v[18:19], v[140:141], v[136:137]
	v_pk_mul_f32 v[18:19], v[30:31], v[76:77] op_sel_hi:[1,0]
	v_pk_fma_f32 v[40:41], v[34:35], v[138:139], v[134:135]
	s_waitcnt vmcnt(16)
; __device__ __forceinline__ void ln_stats(const v4f (&v)[16], float& mean, float& rstd) {
;     float s = 0.f;
; #pragma unroll
;     for (int j = 0; j < 16; ++j) s += (v[j].x + v[j].y) + (v[j].z + v[j].w);
;     mean = wave_sum(s) * (1.f / D_MODEL); float s2 = 0.f;
; __device__ __forceinline__ void phase_ln1(const Ctx& X, const float* r1, const float* g, const float* bt, const float* mod, float* stats, bf16* h2) {
;     ...
;         for (int j = 0; j < 16; ++j) { v[j] = (v[j] - mean) * rstd * gp[64 * j] + bp[64 * j]; if ((j & 3) == 3) asm volatile("" ::: "memory"); }
;         ln_stats(v, mean, rstd);
	v_pk_fma_f32 v[34:35], v[18:19], v[148:149], v[144:145]
	v_pk_mul_f32 v[18:19], v[72:73], v[76:77] op_sel_hi:[1,0]
	v_pk_fma_f32 v[36:37], v[28:29], v[146:147], v[142:143]
	s_waitcnt vmcnt(13)
	v_pk_fma_f32 v[30:31], v[18:19], v[160:161], v[152:153]
	v_pk_mul_f32 v[18:19], v[26:27], v[76:77] op_sel_hi:[1,0]
	v_pk_mul_f32 v[28:29], v[32:33], v[76:77] op_sel_hi:[1,0]
	s_waitcnt vmcnt(12)
	v_pk_fma_f32 v[26:27], v[18:19], v[164:165], v[156:157]
	v_pk_mul_f32 v[18:19], v[22:23], v[76:77] op_sel_hi:[1,0]
	v_mov_b32_e32 v72, v70
	s_waitcnt vmcnt(9)
	v_pk_fma_f32 v[22:23], v[18:19], v[176:177], v[168:169]
	s_waitcnt vmcnt(8)
	v_pk_fma_f32 v[18:19], v[14:15], v[180:181], v[172:173]
	v_pk_mul_f32 v[14:15], v[16:17], v[76:77] op_sel_hi:[1,0]
	v_pk_mul_f32 v[16:17], v[8:9], v[76:77] op_sel_hi:[1,0]
	s_waitcnt vmcnt(4)
	v_pk_fma_f32 v[8:9], v[10:11], v[196:197], v[192:193]
	v_pk_fma_f32 v[10:11], v[16:17], v[194:195], v[190:191]
	v_pk_mul_f32 v[16:17], v[4:5], v[76:77] op_sel_hi:[1,0]
	s_waitcnt vmcnt(2)
	v_pk_fma_f32 v[4:5], v[6:7], v[200:201], v[204:205]
	v_pk_fma_f32 v[6:7], v[16:17], v[198:199], v[202:203]
	v_pk_mul_f32 v[16:17], v[0:1], v[76:77] op_sel_hi:[1,0]
	s_waitcnt vmcnt(0)
	v_pk_fma_f32 v[0:1], v[2:3], v[212:213], v[208:209]
	v_pk_fma_f32 v[2:3], v[16:17], v[210:211], v[206:207]
	v_pk_mov_b32 v[16:17], v[70:71], v[62:63] op_sel:[1,0]
	v_mov_b32_e32 v73, v63
	v_pk_fma_f32 v[32:33], v[28:29], v[158:159], v[150:151]
	v_pk_fma_f32 v[28:29], v[24:25], v[162:163], v[154:155]
	v_pk_fma_f32 v[24:25], v[20:21], v[174:175], v[166:167]
	v_pk_fma_f32 v[20:21], v[12:13], v[178:179], v[170:171]
	v_pk_mul_f32 v[12:13], v[74:75], v[76:77] op_sel_hi:[1,0]
	v_pk_add_f32 v[16:17], v[16:17], v[72:73]
	v_pk_mov_b32 v[72:73], v[60:61], v[58:59] op_sel:[1,0]
	v_mov_b32_e32 v74, v60
	v_mov_b32_e32 v75, v59
	v_pk_add_f32 v[72:73], v[72:73], v[74:75]
	v_add_f32_e32 v16, v16, v17
	v_pk_add_f32 v[72:73], v[72:73], v[72:73] op_sel:[0,1] op_sel_hi:[1,0]
	v_add_f32_e32 v16, 0, v16
	v_add_f32_e32 v74, v56, v57
	v_mov_b32_e32 v17, v52
	v_mov_b32_e32 v73, v53
	v_mov_b32_e32 v75, v50
	v_pk_add_f32 v[16:17], v[16:17], v[72:73]
	v_pk_add_f32 v[72:73], v[74:75], v[86:87]
	v_mov_b32_e32 v74, v48
	v_pk_add_f32 v[16:17], v[16:17], v[72:73]
	v_pk_mov_b32 v[72:73], v[48:49], v[46:47] op_sel:[1,0]
	v_mov_b32_e32 v75, v47
	v_pk_add_f32 v[72:73], v[72:73], v[74:75]
	v_pk_add_f32 v[16:17], v[16:17], v[16:17] op_sel:[0,1] op_sel_hi:[1,0]
	v_pk_add_f32 v[72:73], v[72:73], v[72:73] op_sel:[0,1] op_sel_hi:[1,0]
	v_add_f32_e32 v74, v44, v45
	v_add_f32_e32 v86, v42, v43
	v_mov_b32_e32 v17, v40
	v_mov_b32_e32 v73, v41
	v_mov_b32_e32 v75, v38
	v_mov_b32_e32 v87, v39
	v_pk_add_f32 v[16:17], v[16:17], v[72:73]
	v_pk_add_f32 v[72:73], v[74:75], v[86:87]
	v_mov_b32_e32 v74, v36
	v_pk_add_f32 v[16:17], v[16:17], v[72:73]
	v_pk_mov_b32 v[72:73], v[36:37], v[34:35] op_sel:[1,0]
	v_mov_b32_e32 v75, v35
	v_pk_add_f32 v[72:73], v[72:73], v[74:75]
	v_pk_add_f32 v[16:17], v[16:17], v[16:17] op_sel:[0,1] op_sel_hi:[1,0]
	v_pk_add_f32 v[72:73], v[72:73], v[72:73] op_sel:[0,1] op_sel_hi:[1,0]
	v_add_f32_e32 v74, v32, v33
	v_add_f32_e32 v86, v30, v31
	v_mov_b32_e32 v17, v28
	v_mov_b32_e32 v73, v29
	v_mov_b32_e32 v75, v26
	v_mov_b32_e32 v87, v27
	v_pk_add_f32 v[16:17], v[16:17], v[72:73]
	v_pk_add_f32 v[72:73], v[74:75], v[86:87]
	v_mov_b32_e32 v74, v24
	v_pk_add_f32 v[16:17], v[16:17], v[72:73]
	v_pk_mov_b32 v[72:73], v[24:25], v[22:23] op_sel:[1,0]
	v_mov_b32_e32 v75, v23
	v_pk_add_f32 v[72:73], v[72:73], v[74:75]
	v_pk_fma_f32 v[12:13], v[12:13], v[184:185], v[188:189]
	v_pk_fma_f32 v[14:15], v[14:15], v[182:183], v[186:187]
	v_pk_add_f32 v[16:17], v[16:17], v[16:17] op_sel:[0,1] op_sel_hi:[1,0]
	v_pk_add_f32 v[72:73], v[72:73], v[72:73] op_sel:[0,1] op_sel_hi:[1,0]
	v_add_f32_e32 v74, v20, v21
	v_add_f32_e32 v86, v18, v19
	v_mov_b32_e32 v17, v14
	v_mov_b32_e32 v73, v15
	v_mov_b32_e32 v75, v12
	v_mov_b32_e32 v87, v13
	v_pk_add_f32 v[16:17], v[16:17], v[72:73]
	v_pk_add_f32 v[72:73], v[74:75], v[86:87]
	v_mov_b32_e32 v74, v10
	v_pk_add_f32 v[16:17], v[16:17], v[72:73]
	v_pk_mov_b32 v[72:73], v[10:11], v[8:9] op_sel:[1,0]
	v_mov_b32_e32 v75, v9
	v_pk_add_f32 v[72:73], v[72:73], v[74:75]
	v_pk_add_f32 v[16:17], v[16:17], v[16:17] op_sel:[0,1] op_sel_hi:[1,0]
	v_pk_add_f32 v[72:73], v[72:73], v[72:73] op_sel:[0,1] op_sel_hi:[1,0]
	v_add_f32_e32 v74, v6, v7
	v_add_f32_e32 v86, v4, v5
	v_mov_b32_e32 v17, v2
	v_mov_b32_e32 v73, v3
	v_mov_b32_e32 v75, v0
	v_mov_b32_e32 v87, v1
	v_pk_add_f32 v[16:17], v[16:17], v[72:73]
	v_pk_add_f32 v[72:73], v[74:75], v[86:87]
	v_lshl_add_u64 v[66:67], v[66:67], 0, s[12:13]
	v_pk_add_f32 v[16:17], v[16:17], v[72:73]
	s_nop 0
	v_add_f32_e32 v16, v16, v17
	ds_bpermute_b32 v17, v77, v16
	s_waitcnt lgkmcnt(0)
	v_add_f32_e32 v16, v16, v17
	ds_bpermute_b32 v17, v78, v16
	s_waitcnt lgkmcnt(0)
	v_add_f32_e32 v16, v16, v17
	ds_bpermute_b32 v17, v79, v16
	s_waitcnt lgkmcnt(0)
	v_add_f32_e32 v16, v16, v17
	ds_bpermute_b32 v17, v80, v16
	s_waitcnt lgkmcnt(0)
	v_add_f32_e32 v16, v16, v17
	ds_bpermute_b32 v17, v81, v16
	s_waitcnt lgkmcnt(0)
	v_add_f32_e32 v16, v16, v17
	ds_bpermute_b32 v17, v82, v16
	s_waitcnt lgkmcnt(0)
; __device__ __forceinline__ void ln_stats(const v4f (&v)[16], float& mean, float& rstd) {
;     ...
;     mean = wave_sum(s) * (1.f / D_MODEL); float s2 = 0.f;
; #pragma unroll
;     for (int j = 0; j < 16; ++j) { const v4f d = v[j] - mean; s2 += (d.x * d.x + d.y * d.y) + (d.z * d.z + d.w * d.w); }
;     rstd = 1.0f / sqrtf(wave_sum(s2) * (1.f / D_MODEL) + LN_EPS);
	v_add_f32_e32 v76, v16, v17
	v_fmamk_f32 v71, v76, 0xb9800000, v71
	v_fmac_f32_e32 v70, 0xb9800000, v76
	v_fmamk_f32 v63, v76, 0xb9800000, v63
	v_fmac_f32_e32 v62, 0xb9800000, v76
	v_pk_mul_f32 v[16:17], v[62:63], v[62:63]
	v_pk_mul_f32 v[72:73], v[70:71], v[70:71]
	v_fmamk_f32 v61, v76, 0xb9800000, v61
	v_pk_mov_b32 v[74:75], v[72:73], v[16:17] op_sel:[1,0]
	v_mov_b32_e32 v73, v17
	v_pk_add_f32 v[16:17], v[74:75], v[72:73]
	v_fmac_f32_e32 v60, 0xb9800000, v76
	v_fmamk_f32 v59, v76, 0xb9800000, v59
	v_fmac_f32_e32 v58, 0xb9800000, v76
	v_pk_add_f32 v[16:17], v[16:17], v[16:17] op_sel_hi:[0,1]
	v_pk_mul_f32 v[72:73], v[58:59], v[58:59]
	v_pk_mul_f32 v[74:75], v[60:61], v[60:61]
	v_fmac_f32_e32 v56, 0xb9800000, v76
	v_pk_mov_b32 v[86:87], v[74:75], v[72:73] op_sel:[1,0]
	v_mov_b32_e32 v75, v73
	v_fmamk_f32 v57, v76, 0xb9800000, v57
	v_fmac_f32_e32 v54, 0xb9800000, v76
	v_mul_f32_e32 v16, v56, v56
	v_pk_add_f32 v[72:73], v[86:87], v[74:75]
	v_fmamk_f32 v55, v76, 0xb9800000, v55
	v_pk_fma_f32 v[74:75], v[56:57], v[56:57], v[16:17] op_sel_hi:[1,1,0]
	v_mul_f32_e32 v16, v54, v54
	v_pk_add_f32 v[72:73], v[72:73], v[72:73] op_sel_hi:[0,1]
	v_pk_fma_f32 v[86:87], v[54:55], v[54:55], v[16:17] op_sel_hi:[1,1,0]
	v_fmamk_f32 v51, v76, 0xb9800000, v51
	v_fmac_f32_e32 v50, 0xb9800000, v76
	v_fmamk_f32 v53, v76, 0xb9800000, v53
	v_fmac_f32_e32 v52, 0xb9800000, v76
	v_mul_f32_e32 v74, v52, v52
	v_mul_f32_e32 v86, v53, v53
	v_mul_f32_e32 v16, v50, v50
	v_mul_f32_e32 v72, v51, v51
	v_pk_add_f32 v[74:75], v[74:75], v[86:87]
	v_pk_add_f32 v[16:17], v[16:17], v[72:73]
	v_fmamk_f32 v49, v76, 0xb9800000, v49
	v_pk_add_f32 v[16:17], v[74:75], v[16:17]
	v_fmac_f32_e32 v48, 0xb9800000, v76
	v_fmamk_f32 v47, v76, 0xb9800000, v47
	v_fmac_f32_e32 v46, 0xb9800000, v76
	v_pk_add_f32 v[16:17], v[16:17], v[16:17] op_sel_hi:[0,1]
	v_pk_mul_f32 v[72:73], v[46:47], v[46:47]
	v_pk_mul_f32 v[74:75], v[48:49], v[48:49]
	v_fmac_f32_e32 v44, 0xb9800000, v76
	v_pk_mov_b32 v[86:87], v[74:75], v[72:73] op_sel:[1,0]
	v_mov_b32_e32 v75, v73
	v_fmamk_f32 v45, v76, 0xb9800000, v45
	v_fmac_f32_e32 v42, 0xb9800000, v76
	v_mul_f32_e32 v16, v44, v44
	v_pk_add_f32 v[72:73], v[86:87], v[74:75]
	v_fmamk_f32 v43, v76, 0xb9800000, v43
	v_pk_fma_f32 v[74:75], v[44:45], v[44:45], v[16:17] op_sel_hi:[1,1,0]
	v_mul_f32_e32 v16, v42, v42
	v_pk_add_f32 v[72:73], v[72:73], v[72:73] op_sel_hi:[0,1]
	v_pk_fma_f32 v[86:87], v[42:43], v[42:43], v[16:17] op_sel_hi:[1,1,0]
	v_fmamk_f32 v39, v76, 0xb9800000, v39
	v_fmac_f32_e32 v38, 0xb9800000, v76
	v_fmamk_f32 v41, v76, 0xb9800000, v41
	v_fmac_f32_e32 v40, 0xb9800000, v76
	v_mul_f32_e32 v74, v40, v40
	v_mul_f32_e32 v86, v41, v41
	v_mul_f32_e32 v72, v38, v38
	v_mul_f32_e32 v16, v39, v39
	v_pk_add_f32 v[74:75], v[74:75], v[86:87]
	v_pk_add_f32 v[16:17], v[72:73], v[16:17]
	v_fmamk_f32 v37, v76, 0xb9800000, v37
	v_pk_add_f32 v[16:17], v[74:75], v[16:17]
	v_fmac_f32_e32 v36, 0xb9800000, v76
	v_fmamk_f32 v35, v76, 0xb9800000, v35
	v_fmac_f32_e32 v34, 0xb9800000, v76
	v_pk_add_f32 v[16:17], v[16:17], v[16:17] op_sel_hi:[0,1]
	v_pk_mul_f32 v[72:73], v[34:35], v[34:35]
	v_pk_mul_f32 v[74:75], v[36:37], v[36:37]
	v_fmac_f32_e32 v32, 0xb9800000, v76
	v_pk_mov_b32 v[86:87], v[74:75], v[72:73] op_sel:[1,0]
	v_mov_b32_e32 v75, v73
	v_fmamk_f32 v33, v76, 0xb9800000, v33
	v_fmac_f32_e32 v30, 0xb9800000, v76
	v_mul_f32_e32 v16, v32, v32
	v_pk_add_f32 v[72:73], v[86:87], v[74:75]
	v_fmamk_f32 v31, v76, 0xb9800000, v31
	v_pk_fma_f32 v[74:75], v[32:33], v[32:33], v[16:17] op_sel_hi:[1,1,0]
	v_mul_f32_e32 v16, v30, v30
	v_pk_add_f32 v[72:73], v[72:73], v[72:73] op_sel_hi:[0,1]
	v_pk_fma_f32 v[86:87], v[30:31], v[30:31], v[16:17] op_sel_hi:[1,1,0]
	v_fmamk_f32 v27, v76, 0xb9800000, v27
	v_fmac_f32_e32 v26, 0xb9800000, v76
	v_fmamk_f32 v29, v76, 0xb9800000, v29
	v_fmac_f32_e32 v28, 0xb9800000, v76
	v_mul_f32_e32 v74, v28, v28
	v_mul_f32_e32 v86, v29, v29
	v_mul_f32_e32 v72, v26, v26
	v_mul_f32_e32 v16, v27, v27
	v_pk_add_f32 v[74:75], v[74:75], v[86:87]
	v_pk_add_f32 v[16:17], v[72:73], v[16:17]
	v_fmamk_f32 v25, v76, 0xb9800000, v25
	v_pk_add_f32 v[16:17], v[74:75], v[16:17]
	v_fmac_f32_e32 v24, 0xb9800000, v76
	v_fmamk_f32 v23, v76, 0xb9800000, v23
	v_fmac_f32_e32 v22, 0xb9800000, v76
	v_pk_add_f32 v[16:17], v[16:17], v[16:17] op_sel_hi:[0,1]
	v_pk_mul_f32 v[72:73], v[22:23], v[22:23]
	v_pk_mul_f32 v[74:75], v[24:25], v[24:25]
	v_fmac_f32_e32 v20, 0xb9800000, v76
	v_pk_mov_b32 v[86:87], v[74:75], v[72:73] op_sel:[1,0]
	v_mov_b32_e32 v75, v73
	v_fmamk_f32 v21, v76, 0xb9800000, v21
	v_fmac_f32_e32 v18, 0xb9800000, v76
	v_mul_f32_e32 v16, v20, v20
	v_pk_add_f32 v[72:73], v[86:87], v[74:75]
	v_fmamk_f32 v19, v76, 0xb9800000, v19
	v_pk_fma_f32 v[74:75], v[20:21], v[20:21], v[16:17] op_sel_hi:[1,1,0]
	v_mul_f32_e32 v16, v18, v18
	v_pk_add_f32 v[72:73], v[72:73], v[72:73] op_sel_hi:[0,1]
	v_pk_fma_f32 v[86:87], v[18:19], v[18:19], v[16:17] op_sel_hi:[1,1,0]
	v_fmamk_f32 v13, v76, 0xb9800000, v13
	v_fmac_f32_e32 v12, 0xb9800000, v76
	v_fmamk_f32 v15, v76, 0xb9800000, v15
	v_fmac_f32_e32 v14, 0xb9800000, v76
	v_mul_f32_e32 v74, v14, v14
	v_mul_f32_e32 v86, v15, v15
	v_mul_f32_e32 v72, v12, v12
	v_mul_f32_e32 v16, v13, v13
	v_pk_add_f32 v[74:75], v[74:75], v[86:87]
	v_pk_add_f32 v[16:17], v[72:73], v[16:17]
	v_fmamk_f32 v11, v76, 0xb9800000, v11
	v_pk_add_f32 v[16:17], v[74:75], v[16:17]
	v_fmac_f32_e32 v10, 0xb9800000, v76
	v_fmamk_f32 v9, v76, 0xb9800000, v9
	v_fmac_f32_e32 v8, 0xb9800000, v76
	v_pk_add_f32 v[16:17], v[16:17], v[16:17] op_sel_hi:[0,1]
	v_pk_mul_f32 v[72:73], v[8:9], v[8:9]
	v_pk_mul_f32 v[74:75], v[10:11], v[10:11]
	v_fmac_f32_e32 v6, 0xb9800000, v76
; #define GAS __attribute__((address_space(1)))
; __device__ __forceinline__ unsigned pkbf(float lo, float hi) { unsigned r; asm volatile("v_cvt_pk_bf16_f32 %0, %1, %2" : "=v"(r) : "v"(lo), "v"(hi)); return r; }
; __device__ __forceinline__ void ln_stats(const v4f (&v)[16], float& mean, float& rstd) {
;     ...
;     for (int j = 0; j < 16; ++j) { const v4f d = v[j] - mean; s2 += (d.x * d.x + d.y * d.y) + (d.z * d.z + d.w * d.w); }
;     rstd = 1.0f / sqrtf(wave_sum(s2) * (1.f / D_MODEL) + LN_EPS);
; __device__ __forceinline__ void phase_ln1(const Ctx& X, const float* r1, const float* g, const float* bt, const float* mod, float* stats, bf16* h2) {
;     ...
;         ln_stats(v, mean, rstd);
;         const float* mrow = mod + (size_t)(m / SEQ) * MOD_LD;
;         const GAS v4f* sh = (const GAS v4f*)(mrow + 3 * D_MODEL) + X.lane; const GAS v4f* sc = (const GAS v4f*)(mrow + 4 * D_MODEL) + X.lane;
;         GAS v2u* o = (GAS v2u*)(h2 + (size_t)m * D_MODEL) + X.lane;
; #pragma unroll
;         for (int j = 0; j < 16; ++j) { const v4f y = (v[j] - mean) * rstd * (sc[64 * j] + 1.0f) + sh[64 * j]; v2u w; w.x = pkbf(y.x, y.y); w.y = pkbf(y.z, y.w); o[64 * j] = w; }
	v_pk_mov_b32 v[86:87], v[74:75], v[72:73] op_sel:[1,0]
	v_mov_b32_e32 v75, v73
	v_fmamk_f32 v7, v76, 0xb9800000, v7
	v_fmac_f32_e32 v4, 0xb9800000, v76
	v_mul_f32_e32 v16, v6, v6
	v_pk_add_f32 v[72:73], v[86:87], v[74:75]
	v_fmamk_f32 v5, v76, 0xb9800000, v5
	v_pk_fma_f32 v[74:75], v[6:7], v[6:7], v[16:17] op_sel_hi:[1,1,0]
	v_mul_f32_e32 v16, v4, v4
	v_pk_add_f32 v[72:73], v[72:73], v[72:73] op_sel_hi:[0,1]
	v_pk_fma_f32 v[86:87], v[4:5], v[4:5], v[16:17] op_sel_hi:[1,1,0]
	v_fmamk_f32 v1, v76, 0xb9800000, v1
	v_fmac_f32_e32 v0, 0xb9800000, v76
	v_fmamk_f32 v3, v76, 0xb9800000, v3
	v_fmac_f32_e32 v2, 0xb9800000, v76
	v_mul_f32_e32 v74, v2, v2
	v_mul_f32_e32 v86, v3, v3
	v_mul_f32_e32 v72, v0, v0
	v_mul_f32_e32 v16, v1, v1
	v_pk_add_f32 v[74:75], v[74:75], v[86:87]
	v_pk_add_f32 v[16:17], v[72:73], v[16:17]
	v_lshl_add_u64 v[72:73], s[4:5], 0, v[64:65]
	v_pk_add_f32 v[16:17], v[74:75], v[16:17]
	v_add_co_u32_e32 v74, vcc, s31, v72
	v_add_f32_e32 v16, v16, v17
	s_nop 0
	v_addc_co_u32_e32 v75, vcc, 0, v73, vcc
	v_add_co_u32_e32 v94, vcc, s33, v72
	global_load_dwordx4 v[86:89], v[74:75], off offset:-4096
	s_nop 0
	v_addc_co_u32_e32 v95, vcc, 0, v73, vcc
	global_load_dwordx4 v[90:93], v[94:95], off offset:-4096
	global_load_dwordx4 v[100:103], v64, s[56:57] offset:1024
	global_load_dwordx4 v[104:107], v64, s[64:65] offset:1024
	global_load_dwordx4 v[108:111], v64, s[56:57] offset:2048
	global_load_dwordx4 v[112:115], v64, s[64:65] offset:2048
	global_load_dwordx4 v[116:119], v64, s[56:57] offset:3072
	global_load_dwordx4 v[120:123], v64, s[64:65] offset:3072
	global_load_dwordx4 v[124:127], v64, s[58:59]
	global_load_dwordx4 v[128:131], v64, s[66:67]
	global_load_dwordx4 v[132:135], v64, s[58:59] offset:1024
	global_load_dwordx4 v[136:139], v64, s[66:67] offset:1024
	global_load_dwordx4 v[140:143], v64, s[58:59] offset:2048
	global_load_dwordx4 v[144:147], v64, s[66:67] offset:2048
	global_load_dwordx4 v[148:151], v64, s[58:59] offset:3072
	global_load_dwordx4 v[152:155], v64, s[66:67] offset:3072
	global_load_dwordx4 v[156:159], v64, s[60:61]
	global_load_dwordx4 v[160:163], v64, s[68:69]
	global_load_dwordx4 v[164:167], v64, s[60:61] offset:1024
	global_load_dwordx4 v[168:171], v64, s[68:69] offset:1024
	global_load_dwordx4 v[172:175], v64, s[60:61] offset:2048
	global_load_dwordx4 v[176:179], v64, s[68:69] offset:2048
	global_load_dwordx4 v[180:183], v64, s[60:61] offset:3072
	global_load_dwordx4 v[184:187], v64, s[68:69] offset:3072
	global_load_dwordx4 v[188:191], v64, s[62:63]
	global_load_dwordx4 v[192:195], v64, s[70:71]
	global_load_dwordx4 v[196:199], v64, s[62:63] offset:1024
	global_load_dwordx4 v[200:203], v64, s[70:71] offset:1024
	global_load_dwordx4 v[204:207], v64, s[62:63] offset:2048
	global_load_dwordx4 v[208:211], v64, s[70:71] offset:2048
	global_load_dwordx4 v[212:215], v64, s[62:63] offset:3072
	global_load_dwordx4 v[216:219], v64, s[70:71] offset:3072
	ds_bpermute_b32 v17, v77, v16
	s_waitcnt lgkmcnt(0)
	v_add_f32_e32 v16, v16, v17
	ds_bpermute_b32 v17, v78, v16
	s_waitcnt lgkmcnt(0)
	v_add_f32_e32 v16, v16, v17
	ds_bpermute_b32 v17, v79, v16
	s_waitcnt lgkmcnt(0)
	v_add_f32_e32 v16, v16, v17
	ds_bpermute_b32 v17, v80, v16
	s_waitcnt lgkmcnt(0)
	v_add_f32_e32 v16, v16, v17
	ds_bpermute_b32 v17, v81, v16
	s_waitcnt lgkmcnt(0)
	v_add_f32_e32 v16, v16, v17
	ds_bpermute_b32 v17, v82, v16
	s_waitcnt lgkmcnt(0)
	v_add_f32_e32 v16, v16, v17
	v_fmamk_f32 v16, v16, 0x39800000, v83
	v_mul_f32_e32 v17, 0x4f800000, v16
	v_cmp_gt_f32_e32 vcc, s7, v16
	s_waitcnt vmcnt(31)
	v_pk_add_f32 v[88:89], v[88:89], 1.0 op_sel_hi:[1,0]
	v_cndmask_b32_e32 v16, v16, v17, vcc
	v_sqrt_f32_e32 v17, v16
	v_pk_add_f32 v[86:87], v[86:87], 1.0 op_sel_hi:[1,0]
	v_add_u32_e32 v76, -1, v17
	v_fma_f32 v85, -v76, v17, v16
	v_cmp_ge_f32_e64 s[4:5], 0, v85
	v_add_u32_e32 v85, 1, v17
	s_nop 0
	v_cndmask_b32_e64 v76, v17, v76, s[4:5]
	v_fma_f32 v17, -v85, v17, v16
	v_cmp_lt_f32_e64 s[4:5], 0, v17
	s_nop 1
	v_cndmask_b32_e64 v17, v76, v85, s[4:5]
	v_mul_f32_e32 v76, 0x37800000, v17
	v_cndmask_b32_e32 v17, v17, v76, vcc
	v_cmp_class_f32_e32 vcc, v16, v84
	s_nop 1
	v_cndmask_b32_e32 v16, v17, v16, vcc
	v_div_scale_f32 v17, s[4:5], v16, v16, 1.0
	v_rcp_f32_e32 v76, v17
	s_nop 0
	v_fma_f32 v85, -v17, v76, 1.0
	v_fmac_f32_e32 v76, v85, v76
	v_div_scale_f32 v85, vcc, 1.0, v16, 1.0
	v_mul_f32_e32 v96, v85, v76
	v_fma_f32 v97, -v17, v96, v85
	v_fmac_f32_e32 v96, v97, v76
	v_fma_f32 v17, -v17, v96, v85
	v_div_fmas_f32 v17, v17, v76, v96
	v_div_fixup_f32 v16, v17, v16, 1.0
	v_pk_mul_f32 v[70:71], v[70:71], v[16:17] op_sel_hi:[1,0]
	v_pk_mul_f32 v[62:63], v[62:63], v[16:17] op_sel_hi:[1,0]
	s_waitcnt vmcnt(0)
; #define GAS __attribute__((address_space(1)))
; __device__ __forceinline__ unsigned pkbf(float lo, float hi) { unsigned r; asm volatile("v_cvt_pk_bf16_f32 %0, %1, %2" : "=v"(r) : "v"(lo), "v"(hi)); return r; }
; __device__ __forceinline__ void phase_ln1(const Ctx& X, const float* r1, const float* g, const float* bt, const float* mod, float* stats, bf16* h2) {
;     ...
;         const float* mrow = mod + (size_t)(m / SEQ) * MOD_LD;
;         const GAS v4f* sh = (const GAS v4f*)(mrow + 3 * D_MODEL) + X.lane; const GAS v4f* sc = (const GAS v4f*)(mrow + 4 * D_MODEL) + X.lane;
;         GAS v2u* o = (GAS v2u*)(h2 + (size_t)m * D_MODEL) + X.lane;
; #pragma unroll
;         for (int j = 0; j < 16; ++j) { const v4f y = (v[j] - mean) * rstd * (sc[64 * j] + 1.0f) + sh[64 * j]; v2u w; w.x = pkbf(y.x, y.y); w.y = pkbf(y.z, y.w); o[64 * j] = w; }
	v_pk_fma_f32 v[70:71], v[86:87], v[70:71], v[90:91]
	v_pk_fma_f32 v[62:63], v[88:89], v[62:63], v[92:93]
	v_cvt_pk_bf16_f32 v70, v70, v71
	v_lshl_add_u64 v[96:97], v[72:73], 0, s[18:19]
	v_cvt_pk_bf16_f32 v71, v62, v63
	v_add_co_u32_e32 v62, vcc, s36, v98
	v_pk_mul_f32 v[60:61], v[60:61], v[16:17] op_sel_hi:[1,0]
	s_nop 0
	v_addc_co_u32_e32 v63, vcc, 0, v99, vcc
	global_store_dwordx2 v[62:63], v[70:71], off offset:-4096
	v_lshl_add_u64 v[70:71], v[72:73], 0, s[16:17]
	v_add_co_u32_e32 v98, vcc, s30, v98
	v_pk_mul_f32 v[58:59], v[58:59], v[16:17] op_sel_hi:[1,0]
	s_nop 0
	v_addc_co_u32_e32 v99, vcc, 0, v99, vcc
	v_pk_mul_f32 v[56:57], v[56:57], v[16:17] op_sel_hi:[1,0]
	v_pk_mul_f32 v[54:55], v[54:55], v[16:17] op_sel_hi:[1,0]
	v_pk_mul_f32 v[52:53], v[52:53], v[16:17] op_sel_hi:[1,0]
	v_pk_mul_f32 v[50:51], v[50:51], v[16:17] op_sel_hi:[1,0]
	v_pk_mul_f32 v[48:49], v[48:49], v[16:17] op_sel_hi:[1,0]
	v_pk_mul_f32 v[46:47], v[46:47], v[16:17] op_sel_hi:[1,0]
	v_pk_mul_f32 v[44:45], v[44:45], v[16:17] op_sel_hi:[1,0]
	v_pk_mul_f32 v[42:43], v[42:43], v[16:17] op_sel_hi:[1,0]
	v_pk_mul_f32 v[40:41], v[40:41], v[16:17] op_sel_hi:[1,0]
	v_pk_mul_f32 v[38:39], v[38:39], v[16:17] op_sel_hi:[1,0]
	v_pk_mul_f32 v[36:37], v[36:37], v[16:17] op_sel_hi:[1,0]
	v_pk_mul_f32 v[34:35], v[34:35], v[16:17] op_sel_hi:[1,0]
	v_pk_mul_f32 v[32:33], v[32:33], v[16:17] op_sel_hi:[1,0]
	v_pk_mul_f32 v[30:31], v[30:31], v[16:17] op_sel_hi:[1,0]
	v_pk_mul_f32 v[28:29], v[28:29], v[16:17] op_sel_hi:[1,0]
	v_pk_mul_f32 v[26:27], v[26:27], v[16:17] op_sel_hi:[1,0]
	v_pk_mul_f32 v[24:25], v[24:25], v[16:17] op_sel_hi:[1,0]
	v_pk_mul_f32 v[22:23], v[22:23], v[16:17] op_sel_hi:[1,0]
	v_pk_mul_f32 v[20:21], v[20:21], v[16:17] op_sel_hi:[1,0]
	v_pk_mul_f32 v[18:19], v[18:19], v[16:17] op_sel_hi:[1,0]
	v_pk_mul_f32 v[14:15], v[14:15], v[16:17] op_sel_hi:[1,0]
	v_pk_mul_f32 v[12:13], v[12:13], v[16:17] op_sel_hi:[1,0]
	v_pk_mul_f32 v[10:11], v[10:11], v[16:17] op_sel_hi:[1,0]
	v_pk_mul_f32 v[8:9], v[8:9], v[16:17] op_sel_hi:[1,0]
	v_pk_mul_f32 v[6:7], v[6:7], v[16:17] op_sel_hi:[1,0]
	v_pk_mul_f32 v[4:5], v[4:5], v[16:17] op_sel_hi:[1,0]
	v_pk_mul_f32 v[2:3], v[2:3], v[16:17] op_sel_hi:[1,0]
	v_pk_mul_f32 v[0:1], v[0:1], v[16:17] op_sel_hi:[1,0]
	v_pk_add_f32 v[86:87], v[100:101], 1.0 op_sel_hi:[1,0]
	v_pk_add_f32 v[88:89], v[102:103], 1.0 op_sel_hi:[1,0]
	v_pk_fma_f32 v[60:61], v[86:87], v[60:61], v[104:105]
	v_pk_fma_f32 v[58:59], v[88:89], v[58:59], v[106:107]
	v_cvt_pk_bf16_f32 v60, v60, v61
	s_nop 0
	v_cvt_pk_bf16_f32 v61, v58, v59
	global_store_dwordx2 v[98:99], v[60:61], off offset:512
	s_nop 0
	v_pk_add_f32 v[58:59], v[108:109], 1.0 op_sel_hi:[1,0]
	v_pk_add_f32 v[60:61], v[110:111], 1.0 op_sel_hi:[1,0]
	v_pk_fma_f32 v[56:57], v[58:59], v[56:57], v[112:113]
	v_pk_fma_f32 v[54:55], v[60:61], v[54:55], v[114:115]
	v_cvt_pk_bf16_f32 v56, v56, v57
	s_nop 0
	v_cvt_pk_bf16_f32 v57, v54, v55
	global_store_dwordx2 v[98:99], v[56:57], off offset:1024
	s_nop 0
	v_pk_add_f32 v[54:55], v[116:117], 1.0 op_sel_hi:[1,0]
	v_pk_add_f32 v[56:57], v[118:119], 1.0 op_sel_hi:[1,0]
	v_pk_fma_f32 v[52:53], v[54:55], v[52:53], v[120:121]
	v_pk_fma_f32 v[50:51], v[56:57], v[50:51], v[122:123]
	v_cvt_pk_bf16_f32 v52, v52, v53
	s_nop 0
	v_cvt_pk_bf16_f32 v53, v50, v51
	global_store_dwordx2 v[98:99], v[52:53], off offset:1536
	s_nop 0
	v_pk_add_f32 v[50:51], v[124:125], 1.0 op_sel_hi:[1,0]
	v_pk_add_f32 v[52:53], v[126:127], 1.0 op_sel_hi:[1,0]
	v_pk_fma_f32 v[48:49], v[50:51], v[48:49], v[128:129]
	v_pk_fma_f32 v[46:47], v[52:53], v[46:47], v[130:131]
	v_cvt_pk_bf16_f32 v48, v48, v49
	s_nop 0
	v_cvt_pk_bf16_f32 v49, v46, v47
	global_store_dwordx2 v[98:99], v[48:49], off offset:2048
	s_nop 0
	v_pk_add_f32 v[46:47], v[132:133], 1.0 op_sel_hi:[1,0]
	v_pk_add_f32 v[48:49], v[134:135], 1.0 op_sel_hi:[1,0]
	v_pk_fma_f32 v[44:45], v[46:47], v[44:45], v[136:137]
	v_pk_fma_f32 v[42:43], v[48:49], v[42:43], v[138:139]
	v_cvt_pk_bf16_f32 v44, v44, v45
	s_nop 0
; #define GAS __attribute__((address_space(1)))
; __device__ __forceinline__ unsigned pkbf(float lo, float hi) { unsigned r; asm volatile("v_cvt_pk_bf16_f32 %0, %1, %2" : "=v"(r) : "v"(lo), "v"(hi)); return r; }
; __device__ __forceinline__ void phase_ln1(const Ctx& X, const float* r1, const float* g, const float* bt, const float* mod, float* stats, bf16* h2) {
;     ...
;         const float* mrow = mod + (size_t)(m / SEQ) * MOD_LD;
;         const GAS v4f* sh = (const GAS v4f*)(mrow + 3 * D_MODEL) + X.lane; const GAS v4f* sc = (const GAS v4f*)(mrow + 4 * D_MODEL) + X.lane;
;         GAS v2u* o = (GAS v2u*)(h2 + (size_t)m * D_MODEL) + X.lane;
; #pragma unroll
;         for (int j = 0; j < 16; ++j) { const v4f y = (v[j] - mean) * rstd * (sc[64 * j] + 1.0f) + sh[64 * j]; v2u w; w.x = pkbf(y.x, y.y); w.y = pkbf(y.z, y.w); o[64 * j] = w; }
	v_cvt_pk_bf16_f32 v45, v42, v43
	global_store_dwordx2 v[98:99], v[44:45], off offset:2560
	s_nop 0
	v_pk_add_f32 v[42:43], v[140:141], 1.0 op_sel_hi:[1,0]
	v_pk_add_f32 v[44:45], v[142:143], 1.0 op_sel_hi:[1,0]
	v_pk_fma_f32 v[40:41], v[42:43], v[40:41], v[144:145]
	v_pk_fma_f32 v[38:39], v[44:45], v[38:39], v[146:147]
	v_cvt_pk_bf16_f32 v40, v40, v41
	v_add_co_u32_e32 v46, vcc, s37, v72
	v_cvt_pk_bf16_f32 v41, v38, v39
	global_store_dwordx2 v[98:99], v[40:41], off offset:3072
	s_nop 0
	v_addc_co_u32_e32 v47, vcc, 0, v73, vcc
	v_pk_add_f32 v[38:39], v[148:149], 1.0 op_sel_hi:[1,0]
	v_pk_add_f32 v[40:41], v[150:151], 1.0 op_sel_hi:[1,0]
	v_pk_fma_f32 v[36:37], v[36:37], v[38:39], v[152:153]
	v_pk_fma_f32 v[34:35], v[34:35], v[40:41], v[154:155]
	v_cvt_pk_bf16_f32 v36, v36, v37
	v_add_co_u32_e32 v42, vcc, s38, v72
	v_cvt_pk_bf16_f32 v37, v34, v35
	global_store_dwordx2 v[98:99], v[36:37], off offset:3584
	v_addc_co_u32_e32 v43, vcc, 0, v73, vcc
	v_add_co_u32_e32 v44, vcc, s34, v72
	v_pk_add_f32 v[34:35], v[156:157], 1.0 op_sel_hi:[1,0]
	v_addc_co_u32_e32 v45, vcc, 0, v73, vcc
	v_pk_add_f32 v[36:37], v[158:159], 1.0 op_sel_hi:[1,0]
	v_pk_fma_f32 v[32:33], v[32:33], v[34:35], v[160:161]
	v_pk_fma_f32 v[30:31], v[30:31], v[36:37], v[162:163]
	v_cvt_pk_bf16_f32 v32, v32, v33
	v_add_co_u32_e32 v38, vcc, s35, v72
	v_cvt_pk_bf16_f32 v33, v30, v31
	global_store_dwordx2 v[62:63], v[32:33], off
	v_addc_co_u32_e32 v39, vcc, 0, v73, vcc
	v_pk_add_f32 v[30:31], v[164:165], 1.0 op_sel_hi:[1,0]
	v_pk_add_f32 v[32:33], v[166:167], 1.0 op_sel_hi:[1,0]
	v_pk_fma_f32 v[28:29], v[28:29], v[30:31], v[168:169]
	v_pk_fma_f32 v[26:27], v[26:27], v[32:33], v[170:171]
	v_cvt_pk_bf16_f32 v28, v28, v29
	s_nop 0
	v_cvt_pk_bf16_f32 v29, v26, v27
	global_store_dwordx2 v[62:63], v[28:29], off offset:512
	s_nop 0
	v_pk_add_f32 v[26:27], v[172:173], 1.0 op_sel_hi:[1,0]
	v_pk_add_f32 v[28:29], v[174:175], 1.0 op_sel_hi:[1,0]
	v_pk_fma_f32 v[24:25], v[24:25], v[26:27], v[176:177]
	v_pk_fma_f32 v[22:23], v[22:23], v[28:29], v[178:179]
	v_cvt_pk_bf16_f32 v24, v24, v25
	s_nop 0
	v_cvt_pk_bf16_f32 v25, v22, v23
	global_store_dwordx2 v[62:63], v[24:25], off offset:1024
	s_nop 0
	v_pk_add_f32 v[22:23], v[180:181], 1.0 op_sel_hi:[1,0]
	v_pk_add_f32 v[24:25], v[182:183], 1.0 op_sel_hi:[1,0]
	v_pk_fma_f32 v[20:21], v[20:21], v[22:23], v[184:185]
	v_pk_fma_f32 v[18:19], v[18:19], v[24:25], v[186:187]
	v_cvt_pk_bf16_f32 v20, v20, v21
	s_nop 0
	v_cvt_pk_bf16_f32 v21, v18, v19
	global_store_dwordx2 v[62:63], v[20:21], off offset:1536
	s_nop 0
	v_pk_add_f32 v[18:19], v[188:189], 1.0 op_sel_hi:[1,0]
	v_pk_add_f32 v[20:21], v[190:191], 1.0 op_sel_hi:[1,0]
	v_pk_fma_f32 v[14:15], v[14:15], v[18:19], v[192:193]
	v_pk_fma_f32 v[12:13], v[12:13], v[20:21], v[194:195]
	v_cvt_pk_bf16_f32 v14, v14, v15
	s_nop 0
	v_cvt_pk_bf16_f32 v15, v12, v13
	global_store_dwordx2 v[62:63], v[14:15], off offset:2048
	s_nop 0
	v_pk_add_f32 v[12:13], v[196:197], 1.0 op_sel_hi:[1,0]
	v_pk_add_f32 v[14:15], v[198:199], 1.0 op_sel_hi:[1,0]
	v_pk_fma_f32 v[10:11], v[10:11], v[12:13], v[200:201]
	v_pk_fma_f32 v[8:9], v[8:9], v[14:15], v[202:203]
	v_cvt_pk_bf16_f32 v10, v10, v11
	s_nop 0
	v_cvt_pk_bf16_f32 v11, v8, v9
	global_store_dwordx2 v[62:63], v[10:11], off offset:2560
	s_nop 0
	v_pk_add_f32 v[8:9], v[204:205], 1.0 op_sel_hi:[1,0]
	v_pk_add_f32 v[10:11], v[206:207], 1.0 op_sel_hi:[1,0]
	v_pk_fma_f32 v[6:7], v[6:7], v[8:9], v[208:209]
	v_pk_fma_f32 v[4:5], v[4:5], v[10:11], v[210:211]
	v_cvt_pk_bf16_f32 v6, v6, v7
	s_nop 0
	v_cvt_pk_bf16_f32 v7, v4, v5
	global_store_dwordx2 v[62:63], v[6:7], off offset:3072
	s_nop 0
	v_pk_add_f32 v[4:5], v[212:213], 1.0 op_sel_hi:[1,0]
	v_pk_add_f32 v[6:7], v[214:215], 1.0 op_sel_hi:[1,0]
	v_pk_fma_f32 v[2:3], v[2:3], v[4:5], v[216:217]
	v_pk_fma_f32 v[0:1], v[0:1], v[6:7], v[218:219]
	v_cvt_pk_bf16_f32 v2, v2, v3
	s_nop 0
	v_cvt_pk_bf16_f32 v3, v0, v1
	global_store_dwordx2 v[62:63], v[2:3], off offset:3584
	s_cbranch_scc0 .LBB0_1098
